# +E14 next-layer weight conversion moved out of the gd_prep solve shadow into the P3 group-2 workgroups (range start 9216 -> 0)
# speedup vs baseline: 1.0193x; 1.0074x over previous
; #define LAS __attribute__((address_space(3)))
; __device__ __forceinline__ int tid_fresh() { int t = threadIdx.x; asm volatile("" : "+v"(t)); return t; }
; #define FRESH() ({ CArgs* _p = ka; asm volatile("" : "+s"(_p)); _p; })
; __global__ void __launch_bounds__(512, 2) fwd_kernel(Args args_unused) {
;     ...
;             if (wg >= 64) {
;                 const int NW = G - 64, nA = NW >= 128 ? 32 : 4;
;                 unsigned* ctl = (unsigned*)(ws + WS_CTL); unsigned* c0p = ctl + CW_STAGE + (l * 4 + 0) * 64; unsigned* c1p = c0p + 64;
;                 for (int it = 1024 + wg - 64; it < 3088; it += NW) {
;     ...
;                     if (it < 2048) sample_state_item<false>(FRESH(), lds, l, it - 1024);
;     ...
;                     if (it >= 2048 && it < 3072) sample_state_item<true>(FRESH(), lds, l, it - 2048);
;     ...
;                     if (it >= 3072) rg_prep_item<true>(FRESH(), lds, l, it - 3072);
;                 }
;                 stage_signal(c0p);
;                 const int grp = wg - 64 < nA ? 0 : (wg - 64 < 2 * nA ? 1 : 2);
;                 if (grp == 0) { stage_wait(c0p, (unsigned)NW, ctl + CW_BAR);
;                     for (int t = wg - 64; t < 32; t += nA) sk_mix_task(lds, t, YB, Wbr, PROJ, MIX);
;                     stage_signal(c1p); }
;     ...
;                 for (int it = wg - 64; it < 1024; it += NW) rg_fix_item(FRESH(), l, it);
;     ...
;                 if (grp == 1) { stage_wait(c1p, (unsigned)nA, ctl + CW_BAR);
;                     for (int t = wg - 64 - nA; t < 32; t += nA) sk_resid_task(lds, t, MIX, D, Wout, XB, SSQ); }
;                 if (grp == 2 && l + 1 < DEPTH) { CArgs* ca = FRESH(); const int ctid = tid_fresh(); LAS float* scr = (LAS float*)(lds + (ctid >> 6) * 16640);
;                     for (int it = CONV_SHADOW + (wg - 64 - 2 * nA) * 8 + (ctid >> 6); it < IT_LAYER - (G == 256 ? CONV_P1 : 0); it += (NW - 2 * nA) * 8) conv_item(ca, l + 1, it, scr, ctid & 63); }
.LBB0_171:
	s_add_u32 s56, s50, 0x438a000
	s_addc_u32 s57, s51, 0
	s_add_u32 s58, s50, 0x104000
	s_addc_u32 s59, s51, 0
	s_add_u32 s4, s50, 0x208000
	s_addc_u32 s5, s51, 0
	s_add_u32 s62, s50, 0x2b64a000
	s_addc_u32 s63, s51, 0
	s_add_u32 s64, s50, 0x3ba4a000
	s_addc_u32 s65, s51, 0
	s_add_u32 s92, s50, 0x43c4a000
	s_addc_u32 s93, s51, 0
	s_add_u32 s97, s50, 0x46d0a000
	s_addc_u32 s3, s51, 0
	v_writelane_b32 v253, s4, 7
	s_add_u32 s66, s50, 0x4ae0a000
	s_addc_u32 s67, s51, 0
	v_writelane_b32 v253, s5, 8
	v_writelane_b32 v253, s3, 9
	s_add_u32 s3, s50, 0x640a000
	v_writelane_b32 v253, s3, 10
	s_addc_u32 s3, s51, 0
	s_cmpk_lt_i32 s2, 0x800
	v_writelane_b32 v253, s3, 11
	s_cselect_b64 s[4:5], -1, 0
	v_writelane_b32 v253, s4, 12
	s_ashr_i32 s3, s2, 31
	s_ashr_i32 s47, s46, 31
	v_writelane_b32 v253, s5, 13
	s_lshr_b32 s4, s3, 29
	s_add_i32 s4, s2, s4
	s_ashr_i32 s12, s4, 3
	s_and_b32 s4, s4, -8
	s_sub_i32 s13, s2, s4
	s_lshl_b32 s14, s13, 8
	s_cmpk_lt_i32 s2, 0x182
	s_cselect_b64 s[4:5], -1, 0
	s_add_u32 s72, s50, 0x638a000
	s_addc_u32 s73, s51, 0
	v_writelane_b32 v253, s4, 14
	s_cmpk_lg_i32 s46, 0x100
	s_mov_b32 s81, 0
	v_writelane_b32 v253, s5, 15
	s_cselect_b64 s[4:5], -1, 0
	s_cmpk_lt_i32 s2, 0x82
	s_cselect_b64 s[6:7], -1, 0
	s_or_b64 s[4:5], s[6:7], s[4:5]
	s_add_i32 s6, s74, 0x4260
	v_writelane_b32 v253, s6, 16
	s_mul_hi_i32 s6, s2, 0x55555556
	s_lshr_b32 s7, s6, 31
	s_add_i32 s6, s6, s7
	s_mul_i32 s6, s6, 3
	s_add_i32 s8, s46, 0xbff
	s_sub_i32 s7, s2, s6
	s_cmp_lt_i32 s2, 32
	s_cselect_b64 s[10:11], -1, 0
	v_writelane_b32 v253, s10, 17
	s_ashr_i32 s16, s2, 3
	s_ashr_i32 s17, s16, 31
	v_writelane_b32 v253, s11, 18
	s_mul_i32 s11, s2, 0x1c8000
	s_mov_b32 s10, s16
	v_writelane_b32 v253, s10, 19
	s_lshl_b64 s[16:17], s[16:17], 11
	s_and_b32 s9, s2, 7
	v_writelane_b32 v253, s11, 20
	v_writelane_b32 v253, s16, 21
	s_lshl_b32 s10, s9, 7
	s_lshl_b32 s9, s9, 14
	v_writelane_b32 v253, s17, 22
	v_writelane_b32 v253, s10, 23
	s_lshl_b32 s6, s2, 5
	v_writelane_b32 v253, s9, 24
	s_and_b32 s9, s2, 0xffffffe0
	s_cmp_eq_u32 s9, 32
	s_cselect_b64 s[16:17], -1, 0
	v_writelane_b32 v253, s16, 25
	s_sub_i32 s9, s2, 32
	s_lshr_b32 s10, s9, 3
	v_writelane_b32 v253, s17, 26
	s_lshl_b32 s80, s9, 5
	s_add_i32 s9, s11, 0xfc700000
	v_writelane_b32 v253, s9, 27
	s_lshl_b64 s[16:17], s[80:81], 14
	v_writelane_b32 v253, s16, 28
	s_lshl_b32 s9, s10, 11
	s_mul_hi_i32 s6, s6, 0xe400
	v_writelane_b32 v253, s17, 29
	v_writelane_b32 v253, s9, 30
	s_lshl_b32 s9, s10, 19
	s_cmp_gt_i32 s2, 63
	v_writelane_b32 v253, s9, 31
	s_cselect_b64 s[10:11], -1, 0
	s_sub_i32 s16, s46, 64
	v_writelane_b32 v253, s10, 32
	s_cmpk_gt_i32 s46, 0xbf
	s_cselect_b32 s20, 32, 4
	v_writelane_b32 v253, s11, 33
	s_add_u32 s9, s50, 0x10000
	v_writelane_b32 v253, s9, 34
	s_addc_u32 s9, s51, 0
	s_cmpk_lt_i32 s2, 0x850
	v_writelane_b32 v253, s9, 35
	s_cselect_b64 s[10:11], -1, 0
	s_sub_i32 s17, s2, 64
	s_lshl_b32 s9, s20, 1
	s_cmp_lt_i32 s17, s9
	v_writelane_b32 v253, s10, 36
	s_cselect_b32 s15, 1, 2
	s_cmp_lt_i32 s17, s20
	v_writelane_b32 v253, s11, 37
	s_cselect_b64 s[10:11], -1, 0
	v_writelane_b32 v253, s10, 38
	v_writelane_b32 v255, s20, 0
	v_mov_b32_e32 v2, 0
	v_writelane_b32 v253, s11, 39
	s_and_b64 s[10:11], s[10:11], exec
	s_cselect_b32 s10, 0, s15
	v_writelane_b32 v253, s10, 40
	s_add_u32 s10, s50, 0x4200
	s_addc_u32 s11, s51, 0
	v_writelane_b32 v253, s10, 41
	s_cmpk_lt_i32 s2, 0x60
	s_mul_i32 s15, s13, 0x101
	v_writelane_b32 v253, s11, 42
	s_cselect_b64 s[10:11], -1, 0
	v_writelane_b32 v253, s10, 43
	v_mbcnt_lo_u32_b32 v3, -1, 0
	v_mov_b32_e32 v194, 1
	v_writelane_b32 v253, s11, 44
	s_add_u32 s10, s50, 0x4ce0a000
	s_addc_u32 s11, s51, 0
	v_writelane_b32 v253, s10, 45
	s_cmpk_lt_i32 s2, 0x440
	v_mov_b32_e32 v195, 0x3ecc95a3
	v_writelane_b32 v253, s11, 46
	s_cselect_b64 s[10:11], -1, 0
	v_writelane_b32 v253, s10, 47
	v_mov_b32_e32 v197, 0x3d2aaaab
	v_mov_b64_e32 v[142:143], 0x800
	v_writelane_b32 v253, s11, 48
	s_sub_i32 s10, s17, s9
	s_lshl_b32 s10, s10, 3
	v_writelane_b32 v253, s10, 49
	s_cmpk_eq_i32 s46, 0x100
	s_movk_i32 s10, 0x4670
	s_cselect_b32 s10, s10, 0x4a60
	v_writelane_b32 v253, s10, 50
	s_sub_i32 s9, s16, s9
	v_writelane_b32 v253, s16, 51
	s_lshl_b32 s10, s9, 3
	s_sub_i32 s22, s17, s20
	v_writelane_b32 v253, s10, 52
	s_cmp_lt_i32 s22, 32
	v_writelane_b32 v253, s17, 53
	s_cselect_b64 s[10:11], -1, 0
	v_writelane_b32 v253, s10, 54
	s_cmpk_lt_i32 s2, 0x100
	v_mov_b64_e32 v[144:145], 0x7ff
	v_writelane_b32 v253, s11, 55
	s_cselect_b64 s[10:11], -1, 0
	v_writelane_b32 v253, s10, 56
	v_mbcnt_hi_u32_b32 v196, -1, v3
	v_mov_b32_e32 v252, 0x78
	v_writelane_b32 v253, s11, 57
	s_lshl_b32 s10, s13, 5
	s_cmpk_lt_i32 s2, 0x400
	s_cselect_b64 s[16:17], -1, 0
	s_lshl_b32 s11, s13, 7
	s_add_u32 s90, s50, 0x43a4a000
	s_addc_u32 s91, s51, 0
	s_cmp_lt_i32 s13, 0
	s_cselect_b32 s14, s15, s14
	s_mul_i32 s15, s13, 33
	s_mulk_i32 s13, 0x81
	s_cselect_b32 s10, s15, s10
	s_cselect_b32 s11, s13, s11
	s_add_i32 s13, s14, s12
	s_ashr_i32 s14, s13, 31
	s_lshr_b32 s14, s14, 23
	s_add_i32 s14, s13, s14
	s_and_b32 s15, s14, 0xfe00
	s_sub_i32 s13, s13, s15
	s_sext_i32_i16 s15, s13
	s_bfe_u32 s15, s15, 0x3001c
	v_writelane_b32 v253, s16, 58
	s_add_i32 s15, s13, s15
	s_add_i32 s10, s10, s12
	v_writelane_b32 v253, s17, 59
	s_and_b32 s16, s15, 0xfff8
	s_sub_i32 s13, s13, s16
	s_ashr_i32 s16, s10, 31
	s_lshr_b32 s16, s16, 26
	s_add_i32 s16, s10, s16
	s_and_b32 s17, s16, 0xffc0
	s_sub_i32 s10, s10, s17
	s_bfe_i32 s17, s10, 0x80000
	s_add_i32 s11, s11, s12
	s_bfe_u32 s17, s17, 0x3000c
	s_ashr_i32 s12, s11, 31
	s_add_i32 s17, s10, s17
	s_lshr_b32 s12, s12, 24
	s_and_b32 s18, s17, 0xf8
	s_add_i32 s12, s11, s12
; #define LAS __attribute__((address_space(3)))
; __global__ void __launch_bounds__(512, 2) fwd_kernel(Args args_unused) {
;     ...
;         const int p0 = 1 + 7 * l;
;         const unsigned char* lw = ws + WS_W + (size_t)l * LW_STRIDE;
;         const bf16_t* W1t = (const bf16_t*)(lw + LW_W1); const bf16_t* Wbr = (const bf16_t*)(lw + LW_BR); const bf16_t* Wout = (const bf16_t*)(lw + LW_OUT);
;         const bf16_t* Wup = (const bf16_t*)(lw + LW_UP); const bf16_t* Wdn = (const bf16_t*)(lw + LW_DN);
;         if (IN(p0)) {
;             { pg8::Gemm g{XB, XB, XB, W1t, W1t, W1t, D}; pg8::StaticOrder S; S.init(MP, NPROJ, G, wg, 1); EpiProj E{PROJ, SSQ, (LAS float*)(lds + RING_BYTES), -1};
;     ...
;             if (wg >= 64) {
;                 const int NW = G - 64, nA = NW >= 128 ? 32 : 4;
;                 unsigned* ctl = (unsigned*)(ws + WS_CTL); unsigned* c0p = ctl + CW_STAGE + (l * 4 + 0) * 64; unsigned* c1p = c0p + 64;
;                 for (int it = 1024 + wg - 64; it < 3088; it += NW) {
	s_sub_i32 s10, s10, s18
	s_and_b32 s18, s12, 0xff00
	s_sub_i32 s11, s11, s18
	s_sext_i32_i16 s18, s11
	s_ashr_i32 s14, s14, 9
	s_bfe_u32 s18, s18, 0x3001c
	s_lshl_b32 s14, s14, 3
	s_sext_i32_i16 s13, s13
	s_add_i32 s18, s11, s18
	s_add_i32 s24, s14, s13
	s_ashr_i32 s13, s16, 6
	s_and_b32 s19, s18, 0xfff8
	s_lshl_b32 s13, s13, 3
	s_sext_i32_i8 s10, s10
	s_sub_i32 s11, s11, s19
	s_add_i32 s16, s13, s10
	s_ashr_i32 s10, s12, 8
	s_lshl_b32 s10, s10, 3
	s_sext_i32_i16 s12, s18
	s_sext_i32_i16 s11, s11
	s_add_i32 s18, s10, s11
	s_ashr_i32 s10, s12, 3
	v_writelane_b32 v253, s10, 60
	s_lshr_b32 s10, s12, 3
	s_bfe_i64 s[10:11], s[10:11], 0x100000
	s_bfe_i32 s14, s17, 0x80000
	s_lshl_b64 s[10:11], s[10:11], 20
	s_sext_i32_i16 s14, s14
	v_writelane_b32 v253, s10, 61
	s_sext_i32_i16 s15, s15
	s_lshr_b32 s12, s14, 3
	v_writelane_b32 v253, s11, 62
	s_ashr_i32 s11, s14, 3
	s_ashr_i32 s10, s15, 3
	v_writelane_b32 v254, s11, 0
	s_mov_b32 s14, s18
	s_ashr_i32 s19, s18, 31
	v_writelane_b32 v253, s10, 63
	s_lshr_b32 s10, s15, 3
	v_writelane_b32 v254, s14, 1
	v_mov_b32_e32 v211, 0x68
	v_mov_b32_e32 v200, 0x9450000
	v_writelane_b32 v254, s15, 2
	s_lshl_b64 s[14:15], s[18:19], 20
	s_add_u32 s14, s56, s14
	s_addc_u32 s15, s57, s15
	s_add_u32 s18, s14, 0x80000
	v_writelane_b32 v254, s14, 3
	s_addc_u32 s19, s15, 0
	s_bfe_i64 s[10:11], s[10:11], 0x100000
	v_writelane_b32 v254, s15, 4
	v_writelane_b32 v254, s18, 5
	s_lshl_b64 s[10:11], s[10:11], 20
	s_ashr_i32 s25, s24, 31
	v_writelane_b32 v254, s19, 6
	v_writelane_b32 v254, s10, 7
	v_mov_b32_e32 v201, 0x9410000
	v_mov_b32_e32 v202, 0x2800
	v_writelane_b32 v254, s11, 8
	s_mov_b32 s10, s24
	v_writelane_b32 v254, s10, 9
	v_mov_b32_e32 v203, 0x9000
	v_mov_b32_e32 v204, 0x3db504f3
	v_writelane_b32 v254, s11, 10
	s_lshl_b64 s[10:11], s[24:25], 20
	s_add_u32 s10, s56, s10
	s_addc_u32 s11, s57, s11
	s_add_u32 s14, s10, 0x80000
	v_writelane_b32 v254, s10, 11
	s_addc_u32 s15, s11, 0
	s_ashr_i32 s17, s16, 31
	v_writelane_b32 v254, s11, 12
	v_writelane_b32 v254, s14, 13
	s_bfe_i64 s[10:11], s[12:13], 0x100000
	s_lshl_b64 s[12:13], s[16:17], 19
	v_writelane_b32 v254, s15, 14
	s_lshl_b64 s[14:15], s[10:11], 19
	v_writelane_b32 v254, s14, 15
	s_add_u32 s12, s92, s12
	s_addc_u32 s13, s93, s13
	v_writelane_b32 v254, s15, 16
	s_add_u32 s14, s12, 0x40000
	v_writelane_b32 v254, s12, 17
	s_addc_u32 s15, s13, 0
	v_mov_b32_e32 v205, 0x7f800000
	v_writelane_b32 v254, s13, 18
	v_writelane_b32 v254, s14, 19
	s_lshl_b64 s[12:13], s[16:17], 20
	v_mov_b32_e32 v206, 0x7fc00000
	v_writelane_b32 v254, s15, 20
	s_lshl_b64 s[14:15], s[10:11], 20
	v_writelane_b32 v254, s14, 21
	s_add_u32 s12, s66, s12
	s_addc_u32 s13, s67, s13
	v_writelane_b32 v254, s15, 22
	s_add_u32 s14, s12, 0x80000
	v_writelane_b32 v254, s12, 23
	s_addc_u32 s15, s13, 0
	s_lshl_b64 s[10:11], s[10:11], 22
	v_writelane_b32 v254, s13, 24
	v_writelane_b32 v254, s14, 25
	v_mov_b32_e32 v207, 0xff800000
	v_mov_b32_e32 v208, 0x100
	v_writelane_b32 v254, s15, 26
	v_writelane_b32 v254, s10, 27
	v_mov_b32_e32 v209, 0x41b17218
	v_mov_b32_e32 v146, 0x3f317218
	v_writelane_b32 v254, s11, 28
	s_mov_b32 s10, s16
	v_writelane_b32 v254, s10, 29
	v_mov_b64_e32 v[148:149], 0x100
	v_mov_b64_e32 v[150:151], 0xff
	v_writelane_b32 v254, s11, 30
	s_lshl_b64 s[10:11], s[16:17], 22
	s_add_u32 s10, s64, s10
	s_addc_u32 s11, s65, s11
	s_add_u32 s12, s10, 0x200000
	v_writelane_b32 v254, s10, 31
	s_addc_u32 s13, s11, 0
	v_mov_b64_e32 v[152:153], 0x400
	v_writelane_b32 v254, s11, 32
	s_abs_i32 s10, s46
	v_cvt_f32_u32_e32 v1, s10
	v_writelane_b32 v254, s12, 33
	s_sub_i32 s11, 0, s10
	v_mov_b64_e32 v[154:155], 0x3ff
	v_rcp_iflag_f32_e32 v1, v1
	v_writelane_b32 v254, s13, 34
	v_mov_b32_e32 v210, 0x200
	s_movk_i32 s87, 0x2000
	v_mul_f32_e32 v1, 0x4f7ffffe, v1
	v_cvt_u32_f32_e32 v1, v1
	s_mov_b32 s86, 0x10040
	s_mov_b32 s54, 0x9000
	s_mov_b32 s70, 0x7f800000
	v_readfirstlane_b32 s12, v1
	s_mul_i32 s11, s11, s12
	s_mul_hi_u32 s11, s12, s11
	s_add_i32 s12, s12, s11
	s_abs_i32 s11, s8
	s_mul_hi_u32 s13, s11, s12
	s_mul_i32 s14, s13, s10
	s_sub_i32 s11, s11, s14
	s_xor_b32 s8, s8, s46
	s_ashr_i32 s8, s8, 31
	s_add_i32 s14, s13, 1
	s_sub_i32 s15, s11, s10
	s_cmp_ge_u32 s11, s10
	s_cselect_b32 s13, s14, s13
; #define LAS __attribute__((address_space(3)))
; __device__ __forceinline__ int tid_fresh() { int t = threadIdx.x; asm volatile("" : "+v"(t)); return t; }
; #define FRESH() ({ CArgs* _p = ka; asm volatile("" : "+s"(_p)); _p; })
; __global__ void __launch_bounds__(512, 2) fwd_kernel(Args args_unused) {
;     ...
;             if (wg >= 64) {
;                 const int NW = G - 64, nA = NW >= 128 ? 32 : 4;
;                 unsigned* ctl = (unsigned*)(ws + WS_CTL); unsigned* c0p = ctl + CW_STAGE + (l * 4 + 0) * 64; unsigned* c1p = c0p + 64;
;                 for (int it = 1024 + wg - 64; it < 3088; it += NW) {
;     ...
;                     if (it < 2048) sample_state_item<false>(FRESH(), lds, l, it - 1024);
;     ...
;                     if (it >= 2048 && it < 3072) sample_state_item<true>(FRESH(), lds, l, it - 2048);
;     ...
;                     if (it >= 3072) rg_prep_item<true>(FRESH(), lds, l, it - 3072);
;                 }
;                 stage_signal(c0p);
;                 const int grp = wg - 64 < nA ? 0 : (wg - 64 < 2 * nA ? 1 : 2);
;                 if (grp == 0) { stage_wait(c0p, (unsigned)NW, ctl + CW_BAR);
;                     for (int t = wg - 64; t < 32; t += nA) sk_mix_task(lds, t, YB, Wbr, PROJ, MIX);
;                     stage_signal(c1p); }
;     ...
;                 for (int it = wg - 64; it < 1024; it += NW) rg_fix_item(FRESH(), l, it);
;     ...
;                 if (grp == 1) { stage_wait(c1p, (unsigned)nA, ctl + CW_BAR);
;                     for (int t = wg - 64 - nA; t < 32; t += nA) sk_resid_task(lds, t, MIX, D, Wout, XB, SSQ); }
;                 if (grp == 2 && l + 1 < DEPTH) { CArgs* ca = FRESH(); const int ctid = tid_fresh(); LAS float* scr = (LAS float*)(lds + (ctid >> 6) * 16640);
;                     for (int it = CONV_SHADOW + (wg - 64 - 2 * nA) * 8 + (ctid >> 6); it < IT_LAYER - (G == 256 ? CONV_P1 : 0); it += (NW - 2 * nA) * 8) conv_item(ca, l + 1, it, scr, ctid & 63); }
	s_cselect_b32 s11, s15, s11
	s_add_i32 s14, s13, 1
	s_cmp_ge_u32 s11, s10
	s_cselect_b32 s11, s14, s13
	s_xor_b32 s11, s11, s8
	s_sub_i32 s42, s11, s8
	s_mul_hi_u32 s8, s12, 0xc00
	s_mul_i32 s8, s8, s10
	s_sub_i32 s8, 0xc00, s8
	s_sub_i32 s11, s8, s10
	s_cmp_ge_u32 s8, s10
	s_cselect_b32 s8, s11, s8
	s_sub_i32 s11, s8, s10
	s_cmp_ge_u32 s8, s10
	s_mul_hi_i32 s10, s42, 0x55555556
	s_cselect_b32 s8, s11, s8
	s_lshr_b32 s11, s10, 31
	s_add_i32 s10, s10, s11
	s_mul_i32 s11, s10, 3
	s_sub_i32 s11, s42, s11
	s_or_b32 s8, s8, s11
	s_cmp_eq_u32 s8, 0
	s_mul_i32 s10, s10, s7
	s_cselect_b32 s7, s10, 0
	s_cmp_gt_i32 s42, 0
	v_writelane_b32 v254, s7, 35
	s_cselect_b64 s[10:11], -1, 0
	v_writelane_b32 v254, s10, 36
	s_lshl_b32 s7, s2, 4
	s_lshl_b32 s8, s20, 5
	v_writelane_b32 v254, s11, 37
	s_sub_i32 s7, s7, s8
	s_sub_i32 s7, s7, 0x4800
	v_writelane_b32 v254, s7, 38
	s_lshl_b32 s7, s46, 7
	s_addk_i32 s7, 0xe000
	v_writelane_b32 v254, s7, 39
	s_lshl_b32 s7, s2, 7
	s_add_i32 s8, s7, 0xfffbe000
	v_writelane_b32 v254, s8, 40
	s_addk_i32 s7, 0xe000
	v_writelane_b32 v254, s7, 41
	s_lshl_b32 s7, s2, 9
	s_lshl_b32 s8, s20, 10
	s_sub_i32 s7, s7, s8
	s_sub_i32 s7, s7, 0x90000
	v_writelane_b32 v254, s7, 42
	s_lshl_b32 s7, s9, 9
	v_writelane_b32 v254, s7, 43
	s_lshl_b32 s7, s9, 8
	v_writelane_b32 v254, s7, 44
	s_lshl_b32 s7, s9, 4
	v_writelane_b32 v254, s7, 45
	s_lshl_b32 s7, s2, 10
	v_writelane_b32 v254, s8, 46
	v_writelane_b32 v254, s7, 47
	s_sub_i32 s7, s7, s8
	s_add_i32 s7, s7, 0xffff0200
	v_writelane_b32 v254, s7, 48
	s_lshl_b32 s8, s46, 6
	v_writelane_b32 v254, s8, 49
	s_mul_i32 s8, s2, 9
	s_add_i32 s9, s8, -15
	v_writelane_b32 v254, s9, 50
	s_addk_i32 s8, 0xfef1
	v_writelane_b32 v254, s8, 51
	s_mov_b32 s8, s74
	v_writelane_b32 v254, s8, 52
	s_lshl_b32 s7, s2, 6
	s_ashr_i32 s23, s22, 31
	v_writelane_b32 v254, s9, 53
	s_add_i32 s8, s74, 0xffffbe00
	v_writelane_b32 v254, s8, 54
	s_add_i32 s8, s44, 0xfffffe00
	v_writelane_b32 v254, s8, 55
	v_writelane_b32 v254, s7, 56
	s_addk_i32 s7, 0xf000
	v_writelane_b32 v254, s7, 57
	s_lshl_b32 s7, s20, 6
	v_writelane_b32 v254, s7, 58
	s_lshl_b32 s7, s22, 6
	v_writelane_b32 v254, s7, 59
	s_mov_b32 s8, s22
	v_writelane_b32 v254, s8, 60
	v_mov_b32_e32 v1, 0x358637bd
	s_mov_b32 s71, 0x800000
	v_writelane_b32 v254, s9, 61
	s_lshl_b64 s[8:9], s[22:23], 2
	s_add_u32 s7, s50, s8
	s_addc_u32 s8, s51, s9
	s_add_u32 s10, s7, 0x104000
	s_addc_u32 s11, s8, 0
	s_lshl_b32 s7, s20, 2
	v_writelane_b32 v255, s7, 1
	s_lshl_b32 s7, s2, 2
	v_writelane_b32 v255, s7, 2
	s_lshl_b32 s7, s46, 10
	s_lshl_b64 s[8:9], s[2:3], 2
	v_writelane_b32 v255, s7, 3
	s_add_u32 s7, s50, s8
	v_writelane_b32 v254, s10, 62
	s_addc_u32 s8, s51, s9
	s_mov_b32 s33, 0x3f317217
	v_writelane_b32 v254, s11, 63
	s_add_u32 s10, s7, 0x104000
	s_addc_u32 s11, s8, 0
	v_writelane_b32 v255, s10, 4
	s_xor_b64 s[4:5], s[4:5], -1
	s_mov_b32 s43, 0xbe000000
	v_writelane_b32 v255, s11, 5
	v_writelane_b32 v255, s6, 6
	v_writelane_b32 v255, s4, 7
	s_mov_b64 s[68:69], 0x80
	s_mov_b64 s[84:85], 0x800
	v_writelane_b32 v255, s5, 8
	s_mul_hi_u32 s4, s80, 0xe400
	v_writelane_b32 v255, s4, 9
	s_add_i32 s4, 0, 0x23f20
	v_writelane_b32 v255, s4, 10
	s_add_i32 s4, 0, 0x23f24
	v_writelane_b32 v255, s4, 11
	s_add_i32 s4, 0, 0x8800
	v_writelane_b32 v255, s4, 12
	s_add_i32 s4, 0, 0x10800
	v_writelane_b32 v255, s4, 13
	s_add_i32 s4, 0, 0x14800
	v_writelane_b32 v255, s4, 14
	s_add_i32 s4, 0, 0x14a00
	v_writelane_b32 v255, s4, 15
	s_add_i32 s4, 0, 0x1c400
	v_writelane_b32 v255, s4, 16
	s_add_i32 s4, 0, 0x1c404
	v_writelane_b32 v255, s4, 17
	s_add_i32 s4, 0, 0x1c800
	v_writelane_b32 v255, s4, 18
	s_lshl_b64 s[4:5], s[46:47], 2
	v_writelane_b32 v255, s4, 19
	s_mov_b64 s[48:49], 0x1000
	s_mov_b64 s[82:83], 0x3000
	v_writelane_b32 v255, s5, 20
	s_mov_b64 s[4:5], 0
	v_writelane_b32 v255, s4, 21
	s_mov_b64 s[94:95], 0x3020
	s_mov_b64 s[52:53], 0x5000
	v_writelane_b32 v255, s5, 22
	s_mov_b64 s[4:5], 0
	v_writelane_b32 v255, s4, 23
	s_mov_b32 s96, s81
	s_nop 0
	v_writelane_b32 v255, s5, 24
	v_writelane_b32 v255, s92, 25
	v_writelane_b32 v255, s93, 26
	v_writelane_b32 v255, s97, 27
	v_writelane_b32 v255, s44, 28
	s_mov_b64 s[4:5], 0
	s_nop 0
	v_writelane_b32 v255, s45, 29
	s_branch .LBB0_175

; #define LAS __attribute__((address_space(3)))
; __device__ __forceinline__ void gd_prep_item(CArgs* a, LAS unsigned char* lds, int l, int item) {
;     ...
;         if (CONV_PER > 0 && l + 1 < DEPTH && wid >= 5) {
;             LAS float* scr = (LAS float*)(lds + 84480 + (wid - 5) * 16640); const int base = (item * 3 + (wid - 5)) * CONV_PER;
; #pragma unroll 1
;             for (int k = 0; k < CONV_PER; ++k) conv_item(a, l + 1, base + k, scr, lane); }
.LBB0_912:
	s_or_b64 exec, exec, s[6:7]
	v_readlane_b32 s6, v255, 34
	v_cmp_ne_u32_e32 vcc, 4, v42
	v_readlane_b32 s7, v255, 35
	s_and_b64 s[12:13], s[6:7], vcc
	s_and_saveexec_b64 s[6:7], s[12:13]
	s_branch .LBB0_983
	s_movk_i32 s12, 0x4100
	v_mul_lo_u32 v3, v42, s12
	v_readlane_b32 s12, v255, 15
	v_mul_u32_u24_e32 v4, 0x104, v71
	v_lshrrev_b32_e32 v90, 3, v44
	v_add_u32_e32 v3, s12, v3
	v_add_u32_e32 v3, 0xfffebb00, v3
	v_readlane_b32 s12, v255, 37
	s_add_u32 s18, s36, s12
	v_readlane_b32 s12, v255, 36
	v_add3_u32 v73, v3, v120, v4
	v_lshlrev_b32_e32 v4, 3, v44
	s_addc_u32 s19, s37, s12
	v_and_b32_e32 v72, 56, v4
	s_add_u32 s12, s18, 0x640a000
	v_mul_u32_u24_e32 v4, 0x104, v72
	v_lshlrev_b32_e32 v5, 2, v90
	s_addc_u32 s13, s19, 0
	v_add3_u32 v91, v3, v4, v5
	v_lshlrev_b32_e32 v4, 1, v72
	v_mov_b32_e32 v5, v2
	v_lshl_add_u64 v[74:75], s[12:13], 0, v[4:5]
	s_mov_b64 s[40:41], 0x7410000
	v_lshl_add_u64 v[76:77], v[74:75], 0, s[40:41]
	s_mov_b64 s[40:41], 0x5410000
	v_lshl_add_u64 v[78:79], v[74:75], 0, s[40:41]
	s_mov_b64 s[40:41], 0x4c10000
	v_lshl_add_u64 v[80:81], v[74:75], 0, s[40:41]
	s_add_u32 s40, s18, 0xa41a000
	s_mul_i32 s18, s46, 9
	s_mul_i32 s45, s18, s35
	s_mul_i32 s18, s2, 9
	s_addc_u32 s41, s19, 0
	s_add_i32 s18, s18, s45
	v_lshl_add_u32 v3, v42, 1, v42
	v_add_u32_e32 v99, s18, v3
	s_mul_i32 s18, s46, 0x240
	s_mul_i32 s18, s18, s35
	s_mul_i32 s19, s2, 0x240
	s_add_i32 s19, s19, s18
	s_movk_i32 s18, 0xc0
	v_mul_lo_u32 v4, v42, s18
	v_readlane_b32 s18, v254, 50
	s_add_i32 s18, s18, s45
	v_add_u32_e32 v100, s19, v4
	v_add_lshl_u32 v101, s18, v3, 5
	s_mul_i32 s18, s46, 18
	s_mul_i32 s18, s18, s35
	s_mul_i32 s19, s2, 18
	s_add_i32 s19, s19, s18
	v_mov_b32_e32 v4, s19
	v_mad_u64_u32 v[82:83], s[18:19], v42, 6, v[4:5]
	v_readlane_b32 s18, v254, 51
	s_add_i32 s18, s18, s45
	v_lshlrev_b32_e32 v70, 2, v43
	v_or_b32_e32 v92, 8, v90
	v_or_b32_e32 v93, 16, v90
	v_or_b32_e32 v94, 24, v90
	v_or_b32_e32 v95, 32, v90
	v_or_b32_e32 v96, 40, v90
	v_or_b32_e32 v97, 48, v90
	v_or_b32_e32 v98, 56, v90
	v_add_u32_e32 v83, s18, v3
	s_mov_b32 s35, 0
	s_branch .LBB0_916
